# NSA K/V prefetch 3 tiles ahead (three register sets) instead of 2
# baseline (speedup 1.0000x reference)
.LBB0_733:
	s_or_b64 exec, exec, s[4:5]
	s_add_i32 s74, 0, 0x1e310
	v_mul_f32_e32 v36, v1, v40
	v_mov_b32_e32 v1, s74
	s_waitcnt lgkmcnt(0)
	s_barrier
	ds_read_b32 v1, v1
	s_sub_i32 s0, s78, s2
	s_add_i32 s73, s0, s81
	s_add_i32 s73, s73, 1
	s_movk_i32 s0, 0x200
	s_waitcnt lgkmcnt(0)
	v_readfirstlane_b32 s2, v1
	s_bitcmp0_b32 s2, 8
	s_cselect_b32 s68, 0x100, s0
	s_lshl_b64 s[0:1], s[88:89], 11
	s_lshl_b32 s2, s2, 6
	v_ashrrev_i32_e32 v35, 31, v34
	s_and_b32 s88, s2, 0x3fc0
	v_lshl_add_u64 v[146:147], s[0:1], 0, v[34:35]
	v_readlane_b32 s0, v253, 32
	v_readlane_b32 s2, v253, 34
	v_readlane_b32 s3, v253, 35
	v_pk_mul_f32 v[142:143], v[36:37], v[4:5] op_sel_hi:[0,1]
	v_pk_mul_f32 v[144:145], v[36:37], v[2:3] op_sel_hi:[0,1]
	v_lshl_add_u64 v[2:3], v[146:147], 0, s[88:89]
	v_readlane_b32 s1, v253, 33
	v_mov_b64_e32 v[4:5], s[2:3]
	s_movk_i32 s2, 0x1e00
	v_mad_u64_u32 v[4:5], s[0:1], v2, s2, v[4:5]
	s_mov_b32 s69, 0
	v_mad_i32_i24 v5, v3, s2, v5
	v_lshl_add_u64 v[2:3], v[4:5], 0, s[68:69]
	v_lshlrev_b32_e32 v4, 4, v39
	v_mov_b32_e32 v5, v0
	v_lshl_add_u64 v[2:3], v[2:3], 0, v[4:5]
	s_mov_b64 s[0:1], 0x1900
	v_pk_mul_f32 v[140:141], v[36:37], v[6:7] op_sel_hi:[0,1]
	v_lshl_add_u64 v[6:7], v[2:3], 0, s[0:1]
	v_add_co_u32_e32 v2, vcc, s86, v2
	s_movk_i32 s0, 0x90
	s_nop 0
	v_addc_co_u32_e32 v3, vcc, 0, v3, vcc
	global_load_dwordx4 v[96:99], v[2:3], off offset:2304
	global_load_dwordx4 v[100:103], v[6:7], off offset:128
	v_mul_lo_u32 v1, v34, s0
	s_movk_i32 s0, 0xff72
	v_add_u32_e32 v1, 0, v1
	v_mul_lo_u32 v2, v34, s0
	v_mul_u32_u24_e32 v3, 0x440, v39
	v_pk_mul_f32 v[130:131], v[36:37], v[16:17] op_sel_hi:[0,1]
	v_pk_mul_f32 v[132:133], v[36:37], v[14:15] op_sel_hi:[0,1]
	v_pk_mul_f32 v[134:135], v[36:37], v[12:13] op_sel_hi:[0,1]
	v_pk_mul_f32 v[136:137], v[36:37], v[10:11] op_sel_hi:[0,1]
	v_pk_mul_f32 v[138:139], v[36:37], v[8:9] op_sel_hi:[0,1]
	v_pk_mul_f32 v[114:115], v[36:37], v[32:33] op_sel_hi:[0,1]
	v_pk_mul_f32 v[116:117], v[36:37], v[30:31] op_sel_hi:[0,1]
	v_pk_mul_f32 v[118:119], v[36:37], v[28:29] op_sel_hi:[0,1]
	v_pk_mul_f32 v[120:121], v[36:37], v[26:27] op_sel_hi:[0,1]
	v_pk_mul_f32 v[122:123], v[36:37], v[24:25] op_sel_hi:[0,1]
	v_pk_mul_f32 v[124:125], v[36:37], v[22:23] op_sel_hi:[0,1]
	v_pk_mul_f32 v[126:127], v[36:37], v[20:21] op_sel_hi:[0,1]
	v_pk_mul_f32 v[128:129], v[36:37], v[18:19] op_sel_hi:[0,1]
	v_add_u32_e32 v153, v1, v4
	v_add3_u32 v154, v1, v2, v3
	s_cmp_lt_i32 s73, 1
	v_readlane_b32 s4, v253, 36
	v_readlane_b32 s5, v253, 37
	v_readlane_b32 s6, v253, 38
	v_readlane_b32 s7, v253, 39
	v_readlane_b32 s8, v253, 40
	v_readlane_b32 s9, v253, 41
	v_readlane_b32 s10, v253, 42
	v_readlane_b32 s11, v253, 43
	v_readlane_b32 s12, v253, 44
	v_readlane_b32 s13, v253, 45
	v_readlane_b32 s14, v253, 46
	v_readlane_b32 s15, v253, 47
	s_waitcnt vmcnt(1)
	ds_write_b128 v153, v[96:99]
	s_waitcnt vmcnt(0)
	ds_write_b16 v154, v100 offset:18432
	ds_write_b16_d16_hi v154, v100 offset:18568
	ds_write_b16 v154, v101 offset:18704
	ds_write_b16_d16_hi v154, v101 offset:18840
	ds_write_b16 v154, v102 offset:18976
	ds_write_b16_d16_hi v154, v102 offset:19112
	ds_write_b16 v154, v103 offset:19248
	ds_write_b16_d16_hi v154, v103 offset:19384
	s_waitcnt lgkmcnt(0)
	s_barrier
	s_cbranch_scc1 .LBB0_852
	v_mul_f32_e32 v1, 0xbfb8aa3b, v105
	v_exp_f32_e32 v1, v1
	v_sub_u32_e32 v2, v68, v150
	v_writelane_b32 v254, s41, 25
	v_cmp_gt_i32_e64 s[0:1], 0, v2
	v_add_f32_e32 v1, 1.0, v1
	v_cmp_gt_i32_e64 s[2:3], 35, v2
	v_writelane_b32 v254, s0, 15
	v_rcp_f32_e32 v156, v1
	v_mov_b32_e32 v14, v0
	v_writelane_b32 v254, s1, 16
	v_writelane_b32 v254, s2, 17
	v_mov_b32_e32 v15, v0
	v_lshlrev_b32_e32 v16, 3, v39
	v_writelane_b32 v254, s3, 18
	v_cmp_gt_i32_e64 s[2:3], 8, v2
	v_sub_u32_e32 v155, v150, v67
	v_cmp_gt_i32_e64 s[86:87], 32, v2
	v_cmp_gt_i32_e64 s[94:95], 1, v2
	v_cmp_gt_i32_e64 s[82:83], 33, v2
	v_cmp_gt_i32_e64 s[92:93], 2, v2
	v_cmp_gt_i32_e64 s[96:97], 34, v2
	v_cmp_gt_i32_e64 s[0:1], 3, v2
	v_writelane_b32 v254, s2, 19
	v_cmp_gt_i32_e64 s[20:21], 40, v2
	v_cmp_gt_i32_e64 s[22:23], 9, v2
	v_cmp_gt_i32_e64 s[24:25], 41, v2
	v_cmp_gt_i32_e64 s[26:27], 10, v2
	v_cmp_gt_i32_e64 s[28:29], 42, v2
	v_cmp_gt_i32_e64 s[30:31], 11, v2
	v_cmp_gt_i32_e64 s[34:35], 43, v2
	v_cmp_gt_i32_e64 s[36:37], 16, v2
	v_cmp_gt_i32_e64 s[38:39], 48, v2
	v_cmp_gt_i32_e64 s[40:41], 17, v2
	v_cmp_gt_i32_e64 s[42:43], 49, v2
	v_cmp_gt_i32_e64 s[44:45], 18, v2
	v_cmp_gt_i32_e64 s[46:47], 50, v2
	v_cmp_gt_i32_e64 s[48:49], 19, v2
	v_cmp_gt_i32_e64 s[50:51], 51, v2
	v_cmp_gt_i32_e64 s[52:53], 24, v2
	v_cmp_gt_i32_e64 s[54:55], 56, v2
	v_cmp_gt_i32_e64 s[56:57], 25, v2
	v_cmp_gt_i32_e64 s[58:59], 57, v2
	v_cmp_gt_i32_e64 s[60:61], 26, v2
	v_cmp_gt_i32_e64 s[62:63], 58, v2
	v_cmp_gt_i32_e64 s[64:65], 27, v2
	v_cmp_gt_i32_e64 s[66:67], 59, v2
	v_mul_u32_u24_e32 v158, 0x88, v66
	v_mov_b32_e32 v1, v0
	v_mov_b32_e32 v2, v0
	v_mov_b32_e32 v3, v0
	v_mov_b32_e32 v4, v0
	v_mov_b32_e32 v5, v0
	v_mov_b32_e32 v6, v0
	v_mov_b32_e32 v7, v0
	v_mov_b32_e32 v8, v0
	v_mov_b32_e32 v9, v0
	v_mov_b32_e32 v10, v0
	v_mov_b32_e32 v11, v0
	v_mov_b32_e32 v12, v0
	v_mov_b32_e32 v13, v0
	v_mov_b64_e32 v[78:79], v[14:15]
	v_mov_b64_e32 v[62:63], v[14:15]
	v_mul_u32_u24_e32 v157, 0x90, v37
	v_writelane_b32 v254, s3, 20
	v_mul_u32_u24_e32 v159, 0x88, v37
	v_mov_b32_e32 v161, 0xf149f2ca
	v_mov_b32_e32 v166, 0
	v_lshlrev_b32_e32 v104, 1, v16
	v_mov_b64_e32 v[76:77], v[12:13]
	v_mov_b64_e32 v[74:75], v[10:11]
	v_mov_b64_e32 v[72:73], v[8:9]
	v_mov_b64_e32 v[70:71], v[6:7]
	v_mov_b64_e32 v[68:69], v[4:5]
	v_mov_b64_e32 v[66:67], v[2:3]
	v_mov_b64_e32 v[64:65], v[0:1]
	v_mov_b64_e32 v[60:61], v[12:13]
	v_mov_b64_e32 v[58:59], v[10:11]
	v_mov_b64_e32 v[56:57], v[8:9]
	v_mov_b64_e32 v[54:55], v[6:7]
	v_mov_b64_e32 v[52:53], v[4:5]
	v_mov_b64_e32 v[50:51], v[2:3]
	v_mov_b64_e32 v[48:49], v[0:1]
	s_mov_b32 s98, 0
	s_cmp_lt_i32 s73, 2
	s_cbranch_scc1 .Lnsa_pf_skip
	v_mov_b32_e32 v1, s74
	ds_read_b32 v1, v1 offset:4
	s_movk_i32 s4, 0x200
	s_mov_b32 s91, s89
	v_readlane_b32 s6, v253, 34
	s_waitcnt lgkmcnt(0)
	v_readfirstlane_b32 s68, v1
	s_bitcmp0_b32 s68, 8
	s_cselect_b32 s88, 0x100, s4
	s_lshl_b32 s68, s68, 6
	v_readlane_b32 s7, v253, 35
	s_and_b32 s90, s68, 0x3fc0
	v_lshl_add_u64 v[4:5], v[146:147], 0, s[90:91]
	v_mov_b64_e32 v[2:3], s[6:7]
	s_movk_i32 s4, 0x1e00
	v_mad_u64_u32 v[2:3], s[90:91], v4, s4, v[2:3]
	v_mad_i32_i24 v3, v5, s4, v3
	v_lshl_add_u64 v[2:3], v[2:3], 0, s[88:89]
	v_mov_b32_e32 v105, v0
	v_lshl_add_u64 v[2:3], v[2:3], 0, v[104:105]
	s_mov_b64 s[4:5], 0x1900
	v_lshl_add_u64 v[4:5], v[2:3], 0, s[4:5]
	v_add_co_u32_e32 v2, vcc, 0x1000, v2
	s_nop 1
	v_addc_co_u32_e32 v3, vcc, 0, v3, vcc
	global_load_dwordx4 v[206:209], v[2:3], off offset:2304
	global_load_dwordx4 v[210:213], v[4:5], off offset:128
	s_cmp_lt_i32 s73, 3
	s_cbranch_scc1 .Lnsa_pf_skip
	v_mov_b32_e32 v1, s74
	ds_read_b32 v1, v1 offset:8
	s_movk_i32 s4, 0x200
	s_mov_b32 s91, s89
	v_readlane_b32 s6, v253, 34
	s_waitcnt lgkmcnt(0)
	v_readfirstlane_b32 s68, v1
	s_bitcmp0_b32 s68, 8
	s_cselect_b32 s88, 0x100, s4
	s_lshl_b32 s68, s68, 6
	v_readlane_b32 s7, v253, 35
	s_and_b32 s90, s68, 0x3fc0
	v_lshl_add_u64 v[4:5], v[146:147], 0, s[90:91]
	v_mov_b64_e32 v[2:3], s[6:7]
	s_movk_i32 s4, 0x1e00
	v_mad_u64_u32 v[2:3], s[90:91], v4, s4, v[2:3]
	v_mad_i32_i24 v3, v5, s4, v3
	v_lshl_add_u64 v[2:3], v[2:3], 0, s[88:89]
	v_mov_b32_e32 v105, v0
	v_lshl_add_u64 v[2:3], v[2:3], 0, v[104:105]
	s_mov_b64 s[4:5], 0x1900
	v_lshl_add_u64 v[4:5], v[2:3], 0, s[4:5]
	v_add_co_u32_e32 v2, vcc, 0x1000, v2
	s_nop 1
	v_addc_co_u32_e32 v3, vcc, 0, v3, vcc
	global_load_dwordx4 v[214:217], v[2:3], off offset:2304
	global_load_dwordx4 v[218:221], v[4:5], off offset:128
.Lnsa_pf_skip:
.LBB0_735:
	s_add_i32 s84, s69, 1
	s_cmp_lt_i32 s84, s73
	s_cselect_b64 s[70:71], -1, 0
	s_cmp_ge_i32 s84, s73
	s_cselect_b64 s[2:3], -1, 0
	s_add_i32 s4, s69, 3
	s_cmp_ge_i32 s4, s73
	s_cbranch_scc1 .LBB0_737
	v_mov_b32_e32 v1, s74
	ds_read_b32 v1, v1 offset:12
	v_readlane_b32 s4, v253, 32
	s_movk_i32 s4, 0x200
	s_mov_b32 s91, s89
	v_readlane_b32 s6, v253, 34
	s_waitcnt lgkmcnt(0)
	v_readfirstlane_b32 s68, v1
	s_bitcmp0_b32 s68, 8
	s_cselect_b32 s88, 0x100, s4
	s_lshl_b32 s68, s68, 6
	v_readlane_b32 s7, v253, 35
	s_and_b32 s90, s68, 0x3fc0
	v_lshl_add_u64 v[4:5], v[146:147], 0, s[90:91]
	v_mov_b64_e32 v[2:3], s[6:7]
	s_movk_i32 s4, 0x1e00
	v_mad_u64_u32 v[2:3], s[90:91], v4, s4, v[2:3]
	v_mad_i32_i24 v3, v5, s4, v3
	v_readlane_b32 s5, v253, 33
	v_lshl_add_u64 v[2:3], v[2:3], 0, s[88:89]
	v_mov_b32_e32 v105, v0
	v_lshl_add_u64 v[2:3], v[2:3], 0, v[104:105]
	s_mov_b64 s[4:5], 0x1900
	v_lshl_add_u64 v[4:5], v[2:3], 0, s[4:5]
	v_add_co_u32_e32 v2, vcc, 0x1000, v2
	v_readlane_b32 s8, v253, 36
	s_nop 0
	v_addc_co_u32_e32 v3, vcc, 0, v3, vcc
	s_cmp_eq_u32 s98, 1
	s_cbranch_scc1 .Lnsa_ld_1
	s_cmp_eq_u32 s98, 2
	s_cbranch_scc1 .Lnsa_ld_2
	global_load_dwordx4 v[96:99], v[2:3], off offset:2304
	global_load_dwordx4 v[100:103], v[4:5], off offset:128
	s_branch .Lnsa_ld_done
.Lnsa_ld_1:
	global_load_dwordx4 v[206:209], v[2:3], off offset:2304
	global_load_dwordx4 v[210:213], v[4:5], off offset:128
	s_branch .Lnsa_ld_done
.Lnsa_ld_2:
	global_load_dwordx4 v[214:217], v[2:3], off offset:2304
	global_load_dwordx4 v[218:221], v[4:5], off offset:128

.LBB0_841:
	s_and_b32 s68, s84, 1
	s_mul_i32 s69, s68, 0x2400
	v_add_u32_e32 v1, s69, v153
	s_mulk_i32 s68, 0x2200
	s_add_i32 s69, s84, 2
	s_cmp_lt_i32 s69, s73
	s_cbranch_scc1 .Lnsa_w4
	s_add_i32 s69, s84, 1
	s_cmp_lt_i32 s69, s73
	s_cbranch_scc1 .Lnsa_w2
	s_waitcnt vmcnt(0)
	s_branch .Lnsa_wd
.Lnsa_w2:
	s_waitcnt vmcnt(2)
	s_branch .Lnsa_wd

.Lnsa_wd:
	s_cmp_eq_u32 s98, 0
	s_cbranch_scc1 .Lnsa_sw_1
	s_cmp_eq_u32 s98, 1
	s_cbranch_scc1 .Lnsa_sw_2
	ds_write_b128 v1, v[96:99]
	v_add_u32_e32 v1, s68, v154
	ds_write_b16 v1, v100 offset:18432
	ds_write_b16_d16_hi v1, v100 offset:18568
	ds_write_b16 v1, v101 offset:18704
	ds_write_b16_d16_hi v1, v101 offset:18840
	ds_write_b16 v1, v102 offset:18976
	ds_write_b16_d16_hi v1, v102 offset:19112
	ds_write_b16 v1, v103 offset:19248
	ds_write_b16_d16_hi v1, v103 offset:19384
	s_branch .LBB0_842
.Lnsa_sw_1:
	ds_write_b128 v1, v[206:209]
	v_add_u32_e32 v1, s68, v154
	ds_write_b16 v1, v210 offset:18432
	ds_write_b16_d16_hi v1, v210 offset:18568
	ds_write_b16 v1, v211 offset:18704
	ds_write_b16_d16_hi v1, v211 offset:18840
	ds_write_b16 v1, v212 offset:18976
	ds_write_b16_d16_hi v1, v212 offset:19112
	ds_write_b16 v1, v213 offset:19248
	ds_write_b16_d16_hi v1, v213 offset:19384
	s_branch .LBB0_842
.Lnsa_sw_2:
	ds_write_b128 v1, v[214:217]
	v_add_u32_e32 v1, s68, v154
	ds_write_b16 v1, v218 offset:18432
	ds_write_b16_d16_hi v1, v218 offset:18568
	ds_write_b16 v1, v219 offset:18704
	ds_write_b16_d16_hi v1, v219 offset:18840
	ds_write_b16 v1, v220 offset:18976
	ds_write_b16_d16_hi v1, v220 offset:19112
	ds_write_b16 v1, v221 offset:19248
	ds_write_b16_d16_hi v1, v221 offset:19384
.LBB0_842:
	s_add_i32 s98, s98, 1
	s_cmp_eq_u32 s98, 3
	s_cselect_b32 s98, 0, s98
	s_add_i32 s74, s74, 4
	s_and_b64 vcc, exec, s[2:3]
	s_waitcnt lgkmcnt(0)
	s_barrier
	s_cbranch_vccnz .LBB0_851
	s_mov_b32 s69, s84
	s_branch .LBB0_735
